# G1 rot/plain epilogue stores marked nt (streaming) so the projected rows do not displace GEMM operands in L2
# baseline (speedup 1.0000x reference)
; __device__ __forceinline__ unsigned cvt_pk_bf16(float lo, float hi) { unsigned r; asm volatile("v_cvt_pk_bf16_f32 %0, %1, %2" : "=v"(r) : "v"(lo), "v"(hi)); return r; }
;     __device__ __forceinline__ void operator()(AccT& acc, const Unit& u, int wr, int wc, int fr, int fq) const {
;     ...
; #pragma unroll
;         for (int ai = 0; ai < 2; ++ai)
; #pragma unroll
;             for (int m = 0; m < 4; ++m) { const int row = row0 + ai * 128 + m * 16; bf16_t* rowp = O + (size_t)row * NPROJ + col0;
;                 f32x4 cs0 = (f32x4){1.f, 0.f, 1.f, 0.f}, cs1 = cs0;
;                 if (rot) { const int pos = row < HALF_TOK ? (row & 8191) : ((row - HALF_TOK) & 2047); const f32x2* rp = rope + (size_t)pos * 64 + i0; cs0 = *(const f32x4*)rp; cs1 = *(const f32x4*)(rp + 2); }
; #pragma unroll
;                 for (int bj = 0; bj < 2; ++bj) { f32x4 v0 = acc[ai][bj][m][0], v1 = acc[ai][bj][m][1];
;                     if (rot) { const f32x4 a = v0, b = v1;
;                         v0[0] = a[0] * cs0[0] - a[1] * cs0[1]; v0[1] = a[1] * cs0[0] + a[0] * cs0[1]; v0[2] = a[2] * cs0[2] - a[3] * cs0[3]; v0[3] = a[3] * cs0[2] + a[2] * cs0[3];
;                         v1[0] = b[0] * cs1[0] - b[1] * cs1[1]; v1[1] = b[1] * cs1[0] + b[0] * cs1[1]; v1[2] = b[2] * cs1[2] - b[3] * cs1[3]; v1[3] = b[3] * cs1[2] + b[2] * cs1[3]; }
;                     u32x4 w; w.x = cvt_pk_bf16(v0[0], v0[1]); w.y = cvt_pk_bf16(v0[2], v0[3]); w.z = cvt_pk_bf16(v1[0], v1[1]); w.w = cvt_pk_bf16(v1[2], v1[3]);
;                     *(u32x4*)(rowp + bj * 128) = w; }
;                 __builtin_amdgcn_sched_barrier(0); }
.LBB0_614:
	s_lshl_b32 s2, s24, 8
	v_mov_b32_e32 v190, v169
	v_mov_b32_e32 v0, v187
	s_or_b32 s2, s2, s52
	s_nop 0
	v_lshl_add_u32 v158, v0, 3, s2
	s_and_b32 s2, s24, -4
	s_cmp_eq_u32 s2, 8
	s_mov_b64 s[2:3], -1
	s_cbranch_scc1 .LBB0_680
	s_lshl_b32 s2, s0, 8
	s_add_i32 s2, s2, s38
	v_add_u32_e32 v140, s2, v190
	v_ashrrev_i32_e32 v159, 31, v158
	v_ashrrev_i32_e32 v141, 31, v140
	v_lshlrev_b64 v[142:143], 13, v[140:141]
	v_lshl_add_u64 v[142:143], s[22:23], 0, v[142:143]
	v_lshl_add_u64 v[142:143], v[158:159], 1, v[142:143]
	s_mov_b32 s2, 0x20000
	s_mov_b32 s3, 0
	s_cmp_lt_i32 s24, 4
	s_cbranch_scc1 .Lg1_rot
	v_cvt_pk_bf16_f32 v164, v126, v127
	v_cvt_pk_bf16_f32 v165, v128, v129
	v_cvt_pk_bf16_f32 v166, v110, v111
	v_cvt_pk_bf16_f32 v167, v112, v113
	global_store_dwordx4 v[142:143], v[164:167], off nt
	v_cvt_pk_bf16_f32 v178, v94, v95
	v_cvt_pk_bf16_f32 v179, v96, v97
	v_cvt_pk_bf16_f32 v180, v78, v79
	v_cvt_pk_bf16_f32 v181, v80, v81
	global_store_dwordx4 v[142:143], v[178:181], off offset:256 nt
	v_lshl_add_u64 v[144:145], v[142:143], 0, s[2:3]
	v_cvt_pk_bf16_f32 v164, v122, v123
	v_cvt_pk_bf16_f32 v165, v124, v125
	v_cvt_pk_bf16_f32 v166, v106, v107
	v_cvt_pk_bf16_f32 v167, v108, v109
	global_store_dwordx4 v[144:145], v[164:167], off nt
	v_cvt_pk_bf16_f32 v178, v90, v91
	v_cvt_pk_bf16_f32 v179, v92, v93
	v_cvt_pk_bf16_f32 v180, v74, v75
	v_cvt_pk_bf16_f32 v181, v76, v77
	global_store_dwordx4 v[144:145], v[178:181], off offset:256 nt
	v_lshl_add_u64 v[142:143], v[144:145], 0, s[2:3]
	v_cvt_pk_bf16_f32 v164, v118, v119
	v_cvt_pk_bf16_f32 v165, v120, v121
	v_cvt_pk_bf16_f32 v166, v102, v103
	v_cvt_pk_bf16_f32 v167, v104, v105
	global_store_dwordx4 v[142:143], v[164:167], off nt
	v_cvt_pk_bf16_f32 v178, v86, v87
	v_cvt_pk_bf16_f32 v179, v88, v89
	v_cvt_pk_bf16_f32 v180, v70, v71
	v_cvt_pk_bf16_f32 v181, v72, v73
	global_store_dwordx4 v[142:143], v[178:181], off offset:256 nt
	v_lshl_add_u64 v[144:145], v[142:143], 0, s[2:3]
	v_cvt_pk_bf16_f32 v164, v114, v115
	v_cvt_pk_bf16_f32 v165, v116, v117
	v_cvt_pk_bf16_f32 v166, v98, v99
	v_cvt_pk_bf16_f32 v167, v100, v101
	global_store_dwordx4 v[144:145], v[164:167], off nt
	v_cvt_pk_bf16_f32 v178, v82, v83
	v_cvt_pk_bf16_f32 v179, v84, v85
	v_cvt_pk_bf16_f32 v180, v66, v67
	v_cvt_pk_bf16_f32 v181, v68, v69
	global_store_dwordx4 v[144:145], v[178:181], off offset:256 nt
	v_lshl_add_u64 v[142:143], v[144:145], 0, s[2:3]
	v_lshl_add_u64 v[142:143], v[142:143], 0, s[2:3]
	v_lshl_add_u64 v[142:143], v[142:143], 0, s[2:3]
	v_lshl_add_u64 v[142:143], v[142:143], 0, s[2:3]
	v_lshl_add_u64 v[142:143], v[142:143], 0, s[2:3]
	v_cvt_pk_bf16_f32 v164, v62, v63
	v_cvt_pk_bf16_f32 v165, v64, v65
	v_cvt_pk_bf16_f32 v166, v46, v47
	v_cvt_pk_bf16_f32 v167, v48, v49
	global_store_dwordx4 v[142:143], v[164:167], off nt
	v_cvt_pk_bf16_f32 v178, v30, v31
	v_cvt_pk_bf16_f32 v179, v32, v33
	v_cvt_pk_bf16_f32 v180, v14, v15
	v_cvt_pk_bf16_f32 v181, v16, v17
	global_store_dwordx4 v[142:143], v[178:181], off offset:256 nt
	v_lshl_add_u64 v[144:145], v[142:143], 0, s[2:3]
	v_cvt_pk_bf16_f32 v164, v58, v59
	v_cvt_pk_bf16_f32 v165, v60, v61
	v_cvt_pk_bf16_f32 v166, v42, v43
	v_cvt_pk_bf16_f32 v167, v44, v45
	global_store_dwordx4 v[144:145], v[164:167], off nt
	v_cvt_pk_bf16_f32 v178, v26, v27
	v_cvt_pk_bf16_f32 v179, v28, v29
	v_cvt_pk_bf16_f32 v180, v10, v11
	v_cvt_pk_bf16_f32 v181, v12, v13
	global_store_dwordx4 v[144:145], v[178:181], off offset:256 nt
	v_lshl_add_u64 v[142:143], v[144:145], 0, s[2:3]
	v_cvt_pk_bf16_f32 v164, v54, v55
	v_cvt_pk_bf16_f32 v165, v56, v57
	v_cvt_pk_bf16_f32 v166, v38, v39
	v_cvt_pk_bf16_f32 v167, v40, v41
	global_store_dwordx4 v[142:143], v[164:167], off nt
	v_cvt_pk_bf16_f32 v178, v22, v23
	v_cvt_pk_bf16_f32 v179, v24, v25
	v_cvt_pk_bf16_f32 v180, v6, v7
	v_cvt_pk_bf16_f32 v181, v8, v9
	global_store_dwordx4 v[142:143], v[178:181], off offset:256 nt
	v_lshl_add_u64 v[144:145], v[142:143], 0, s[2:3]
	v_cvt_pk_bf16_f32 v164, v50, v51
	v_cvt_pk_bf16_f32 v165, v52, v53
	v_cvt_pk_bf16_f32 v166, v34, v35
	v_cvt_pk_bf16_f32 v167, v36, v37
	global_store_dwordx4 v[144:145], v[164:167], off nt
	v_cvt_pk_bf16_f32 v178, v18, v19
	v_cvt_pk_bf16_f32 v179, v20, v21
	v_cvt_pk_bf16_f32 v180, v2, v3
	v_cvt_pk_bf16_f32 v181, v4, v5
	global_store_dwordx4 v[144:145], v[178:181], off offset:256 nt
	s_branch .Lg1_epi_done
;     __device__ __forceinline__ void operator()(AccT& acc, const Unit& u, int wr, int wc, int fr, int fq) const {
;     ...
;             for (int m = 0; m < 4; ++m) { const int row = row0 + ai * 128 + m * 16; bf16_t* rowp = O + (size_t)row * NPROJ + col0;
;                 f32x4 cs0 = (f32x4){1.f, 0.f, 1.f, 0.f}, cs1 = cs0;
;                 if (rot) { const int pos = row < HALF_TOK ? (row & 8191) : ((row - HALF_TOK) & 2047); const f32x2* rp = rope + (size_t)pos * 64 + i0; cs0 = *(const f32x4*)rp; cs1 = *(const f32x4*)(rp + 2); }
; #pragma unroll
;                 for (int bj = 0; bj < 2; ++bj) { f32x4 v0 = acc[ai][bj][m][0], v1 = acc[ai][bj][m][1];
;                     if (rot) { const f32x4 a = v0, b = v1;
;                         v0[0] = a[0] * cs0[0] - a[1] * cs0[1]; v0[1] = a[1] * cs0[0] + a[0] * cs0[1]; v0[2] = a[2] * cs0[2] - a[3] * cs0[3]; v0[3] = a[3] * cs0[2] + a[2] * cs0[3];
;                         v1[0] = b[0] * cs1[0] - b[1] * cs1[1]; v1[1] = b[1] * cs1[0] + b[0] * cs1[1]; v1[2] = b[2] * cs1[2] - b[3] * cs1[3]; v1[3] = b[3] * cs1[2] + b[2] * cs1[3]; }
.Lg1_rot:
	s_movk_i32 s4, 0x4000
	v_lshl_add_u32 v138, v0, 2, s79
	v_cmp_gt_i32_e32 vcc, s4, v140
	v_mov_b32_e32 v0, 0x7ff
	v_mov_b32_e32 v160, 0x1fff
	v_ashrrev_i32_e32 v139, 31, v138
	v_cndmask_b32_e32 v0, v0, v160, vcc
	v_and_b32_e32 v0, v0, v140
	v_lshlrev_b32_e32 v0, 9, v0
	v_lshl_add_u64 v[160:161], s[46:47], 0, v[0:1]
	v_lshl_add_u64 v[138:139], v[138:139], 3, v[160:161]
	s_mov_b32 s42, 0x2000
	s_mov_b32 s43, 0
	global_load_dwordx4 v[134:137], v[138:139], off
	global_load_dwordx4 v[130:133], v[138:139], off offset:16
	s_nop 0
	v_lshl_add_u64 v[138:139], v[138:139], 0, s[42:43]
	global_load_dwordx4 v[182:185], v[138:139], off
	global_load_dwordx4 v[192:195], v[138:139], off offset:16
	s_nop 0
	v_lshl_add_u64 v[138:139], v[138:139], 0, s[42:43]
	global_load_dwordx4 v[196:199], v[138:139], off
	global_load_dwordx4 v[204:207], v[138:139], off offset:16
	s_nop 0
	v_lshl_add_u64 v[138:139], v[138:139], 0, s[42:43]
	global_load_dwordx4 v[222:225], v[138:139], off
	global_load_dwordx4 v[226:229], v[138:139], off offset:16
	s_nop 0
	v_lshl_add_u64 v[138:139], v[138:139], 0, s[42:43]
	v_lshl_add_u64 v[138:139], v[138:139], 0, s[42:43]
	v_lshl_add_u64 v[138:139], v[138:139], 0, s[42:43]
	v_lshl_add_u64 v[138:139], v[138:139], 0, s[42:43]
	v_lshl_add_u64 v[138:139], v[138:139], 0, s[42:43]
	s_waitcnt vmcnt(6)
	v_mul_f32_e32 v0, v127, v135
	v_mul_f32_e32 v172, v111, v131
	v_mul_f32_e32 v160, v126, v135
	v_mul_f32_e32 v173, v110, v131
	v_mul_f32_e32 v161, v126, v134
	v_mul_f32_e32 v174, v110, v130
	v_mul_f32_e32 v170, v137, v129
	v_mul_f32_e32 v175, v133, v113
	v_mul_f32_e32 v171, v128, v137
	v_mul_f32_e32 v176, v112, v133
	v_fma_f32 v127, v127, v134, v160
	v_fma_f32 v111, v111, v130, v173
	v_sub_f32_e32 v126, v161, v0
	v_sub_f32_e32 v110, v174, v172
	v_fma_f32 v128, v136, v128, -v170
	v_fma_f32 v112, v132, v112, -v175
	v_fma_f32 v129, v129, v136, v171
	v_fma_f32 v113, v113, v132, v176
	v_mul_f32_e32 v0, v95, v135
	v_mul_f32_e32 v172, v79, v131
	v_mul_f32_e32 v160, v94, v135
	v_mul_f32_e32 v173, v78, v131
	v_mul_f32_e32 v161, v94, v134
	v_mul_f32_e32 v174, v78, v130
	v_mul_f32_e32 v170, v137, v97
	v_mul_f32_e32 v175, v133, v81
	v_mul_f32_e32 v171, v96, v137
	v_mul_f32_e32 v176, v80, v133
	v_fma_f32 v95, v95, v134, v160
	v_fma_f32 v79, v79, v130, v173
	v_sub_f32_e32 v94, v161, v0
	v_sub_f32_e32 v78, v174, v172
	v_fma_f32 v96, v136, v96, -v170
	v_fma_f32 v80, v132, v80, -v175
	v_fma_f32 v97, v97, v136, v171
	v_fma_f32 v81, v81, v132, v176
	global_load_dwordx4 v[134:137], v[138:139], off
	global_load_dwordx4 v[130:133], v[138:139], off offset:16
	s_nop 0
	v_lshl_add_u64 v[138:139], v[138:139], 0, s[42:43]
	s_waitcnt vmcnt(6)
	v_mul_f32_e32 v0, v123, v183
	v_mul_f32_e32 v172, v107, v193
	v_mul_f32_e32 v160, v122, v183
	v_mul_f32_e32 v173, v106, v193
	v_mul_f32_e32 v161, v122, v182
	v_mul_f32_e32 v174, v106, v192
	v_mul_f32_e32 v170, v185, v125
	v_mul_f32_e32 v175, v195, v109
	v_mul_f32_e32 v171, v124, v185
	v_mul_f32_e32 v176, v108, v195
	v_fma_f32 v123, v123, v182, v160
	v_fma_f32 v107, v107, v192, v173
	v_sub_f32_e32 v122, v161, v0
	v_sub_f32_e32 v106, v174, v172
	v_fma_f32 v124, v184, v124, -v170
	v_fma_f32 v108, v194, v108, -v175
	v_fma_f32 v125, v125, v184, v171
	v_fma_f32 v109, v109, v194, v176
	v_mul_f32_e32 v0, v91, v183
	v_mul_f32_e32 v172, v75, v193
	v_mul_f32_e32 v160, v90, v183
	v_mul_f32_e32 v173, v74, v193
	v_mul_f32_e32 v161, v90, v182
	v_mul_f32_e32 v174, v74, v192
	v_mul_f32_e32 v170, v185, v93
	v_mul_f32_e32 v175, v195, v77
	v_mul_f32_e32 v171, v92, v185
	v_mul_f32_e32 v176, v76, v195
	v_fma_f32 v91, v91, v182, v160
	v_fma_f32 v75, v75, v192, v173
	v_sub_f32_e32 v90, v161, v0
	v_sub_f32_e32 v74, v174, v172
	v_fma_f32 v92, v184, v92, -v170
	v_fma_f32 v76, v194, v76, -v175
	v_fma_f32 v93, v93, v184, v171
	v_fma_f32 v77, v77, v194, v176
	global_load_dwordx4 v[182:185], v[138:139], off
	global_load_dwordx4 v[192:195], v[138:139], off offset:16
	s_nop 0
	v_lshl_add_u64 v[138:139], v[138:139], 0, s[42:43]
	s_waitcnt vmcnt(6)
	v_mul_f32_e32 v0, v119, v197
	v_mul_f32_e32 v172, v103, v205
	v_mul_f32_e32 v160, v118, v197
	v_mul_f32_e32 v173, v102, v205
	v_mul_f32_e32 v161, v118, v196
	v_mul_f32_e32 v174, v102, v204
	v_mul_f32_e32 v170, v199, v121
	v_mul_f32_e32 v175, v207, v105
	v_mul_f32_e32 v171, v120, v199
	v_mul_f32_e32 v176, v104, v207
	v_fma_f32 v119, v119, v196, v160
	v_fma_f32 v103, v103, v204, v173
	v_sub_f32_e32 v118, v161, v0
	v_sub_f32_e32 v102, v174, v172
	v_fma_f32 v120, v198, v120, -v170
	v_fma_f32 v104, v206, v104, -v175
	v_fma_f32 v121, v121, v198, v171
	v_fma_f32 v105, v105, v206, v176
	v_mul_f32_e32 v0, v87, v197
	v_mul_f32_e32 v172, v71, v205
	v_mul_f32_e32 v160, v86, v197
	v_mul_f32_e32 v173, v70, v205
	v_mul_f32_e32 v161, v86, v196
	v_mul_f32_e32 v174, v70, v204
	v_mul_f32_e32 v170, v199, v89
	v_mul_f32_e32 v175, v207, v73
	v_mul_f32_e32 v171, v88, v199
	v_mul_f32_e32 v176, v72, v207
	v_fma_f32 v87, v87, v196, v160
	v_fma_f32 v71, v71, v204, v173
	v_sub_f32_e32 v86, v161, v0
	v_sub_f32_e32 v70, v174, v172
	v_fma_f32 v88, v198, v88, -v170
	v_fma_f32 v72, v206, v72, -v175
	v_fma_f32 v89, v89, v198, v171
	v_fma_f32 v73, v73, v206, v176
	global_load_dwordx4 v[196:199], v[138:139], off
	global_load_dwordx4 v[204:207], v[138:139], off offset:16
	s_nop 0
	v_lshl_add_u64 v[138:139], v[138:139], 0, s[42:43]
	s_waitcnt vmcnt(6)
;     __device__ __forceinline__ void operator()(AccT& acc, const Unit& u, int wr, int wc, int fr, int fq) const {
;     ...
;                     if (rot) { const f32x4 a = v0, b = v1;
;                         v0[0] = a[0] * cs0[0] - a[1] * cs0[1]; v0[1] = a[1] * cs0[0] + a[0] * cs0[1]; v0[2] = a[2] * cs0[2] - a[3] * cs0[3]; v0[3] = a[3] * cs0[2] + a[2] * cs0[3];
;                         v1[0] = b[0] * cs1[0] - b[1] * cs1[1]; v1[1] = b[1] * cs1[0] + b[0] * cs1[1]; v1[2] = b[2] * cs1[2] - b[3] * cs1[3]; v1[3] = b[3] * cs1[2] + b[2] * cs1[3]; }
	v_mul_f32_e32 v0, v115, v223
	v_mul_f32_e32 v172, v99, v227
	v_mul_f32_e32 v160, v114, v223
	v_mul_f32_e32 v173, v98, v227
	v_mul_f32_e32 v161, v114, v222
	v_mul_f32_e32 v174, v98, v226
	v_mul_f32_e32 v170, v225, v117
	v_mul_f32_e32 v175, v229, v101
	v_mul_f32_e32 v171, v116, v225
	v_mul_f32_e32 v176, v100, v229
	v_fma_f32 v115, v115, v222, v160
	v_fma_f32 v99, v99, v226, v173
	v_sub_f32_e32 v114, v161, v0
	v_sub_f32_e32 v98, v174, v172
	v_fma_f32 v116, v224, v116, -v170
	v_fma_f32 v100, v228, v100, -v175
	v_fma_f32 v117, v117, v224, v171
	v_fma_f32 v101, v101, v228, v176
	v_mul_f32_e32 v0, v83, v223
	v_mul_f32_e32 v172, v67, v227
	v_mul_f32_e32 v160, v82, v223
	v_mul_f32_e32 v173, v66, v227
	v_mul_f32_e32 v161, v82, v222
	v_mul_f32_e32 v174, v66, v226
	v_mul_f32_e32 v170, v225, v85
	v_mul_f32_e32 v175, v229, v69
	v_mul_f32_e32 v171, v84, v225
	v_mul_f32_e32 v176, v68, v229
	v_fma_f32 v83, v83, v222, v160
	v_fma_f32 v67, v67, v226, v173
	v_sub_f32_e32 v82, v161, v0
	v_sub_f32_e32 v66, v174, v172
	v_fma_f32 v84, v224, v84, -v170
	v_fma_f32 v68, v228, v68, -v175
	v_fma_f32 v85, v85, v224, v171
	v_fma_f32 v69, v69, v228, v176
	global_load_dwordx4 v[222:225], v[138:139], off
	global_load_dwordx4 v[226:229], v[138:139], off offset:16
	s_waitcnt vmcnt(6)
	v_mul_f32_e32 v0, v63, v135
	v_mul_f32_e32 v172, v47, v131
	v_mul_f32_e32 v160, v62, v135
	v_mul_f32_e32 v173, v46, v131
	v_mul_f32_e32 v161, v62, v134
	v_mul_f32_e32 v174, v46, v130
	v_mul_f32_e32 v170, v137, v65
	v_mul_f32_e32 v175, v133, v49
	v_mul_f32_e32 v171, v64, v137
	v_mul_f32_e32 v176, v48, v133
	v_fma_f32 v63, v63, v134, v160
	v_fma_f32 v47, v47, v130, v173
	v_sub_f32_e32 v62, v161, v0
	v_sub_f32_e32 v46, v174, v172
	v_fma_f32 v64, v136, v64, -v170
	v_fma_f32 v48, v132, v48, -v175
	v_fma_f32 v65, v65, v136, v171
	v_fma_f32 v49, v49, v132, v176
	v_mul_f32_e32 v0, v31, v135
	v_mul_f32_e32 v172, v15, v131
	v_mul_f32_e32 v160, v30, v135
	v_mul_f32_e32 v173, v14, v131
	v_mul_f32_e32 v161, v30, v134
	v_mul_f32_e32 v174, v14, v130
	v_mul_f32_e32 v170, v137, v33
	v_mul_f32_e32 v175, v133, v17
	v_mul_f32_e32 v171, v32, v137
	v_mul_f32_e32 v176, v16, v133
	v_fma_f32 v31, v31, v134, v160
	v_fma_f32 v15, v15, v130, v173
	v_sub_f32_e32 v30, v161, v0
	v_sub_f32_e32 v14, v174, v172
	v_fma_f32 v32, v136, v32, -v170
	v_fma_f32 v16, v132, v16, -v175
	v_fma_f32 v33, v33, v136, v171
	v_fma_f32 v17, v17, v132, v176
	s_waitcnt vmcnt(4)
	v_mul_f32_e32 v0, v59, v183
	v_mul_f32_e32 v172, v43, v193
	v_mul_f32_e32 v160, v58, v183
	v_mul_f32_e32 v173, v42, v193
	v_mul_f32_e32 v161, v58, v182
	v_mul_f32_e32 v174, v42, v192
	v_mul_f32_e32 v170, v185, v61
	v_mul_f32_e32 v175, v195, v45
	v_mul_f32_e32 v171, v60, v185
	v_mul_f32_e32 v176, v44, v195
	v_fma_f32 v59, v59, v182, v160
	v_fma_f32 v43, v43, v192, v173
	v_sub_f32_e32 v58, v161, v0
	v_sub_f32_e32 v42, v174, v172
	v_fma_f32 v60, v184, v60, -v170
	v_fma_f32 v44, v194, v44, -v175
	v_fma_f32 v61, v61, v184, v171
	v_fma_f32 v45, v45, v194, v176
	v_mul_f32_e32 v0, v27, v183
	v_mul_f32_e32 v172, v11, v193
	v_mul_f32_e32 v160, v26, v183
	v_mul_f32_e32 v173, v10, v193
	v_mul_f32_e32 v161, v26, v182
	v_mul_f32_e32 v174, v10, v192
	v_mul_f32_e32 v170, v185, v29
	v_mul_f32_e32 v175, v195, v13
	v_mul_f32_e32 v171, v28, v185
	v_mul_f32_e32 v176, v12, v195
	v_fma_f32 v27, v27, v182, v160
	v_fma_f32 v11, v11, v192, v173
	v_sub_f32_e32 v26, v161, v0
	v_sub_f32_e32 v10, v174, v172
	v_fma_f32 v28, v184, v28, -v170
	v_fma_f32 v12, v194, v12, -v175
	v_fma_f32 v29, v29, v184, v171
	v_fma_f32 v13, v13, v194, v176
	s_waitcnt vmcnt(2)
	v_mul_f32_e32 v0, v55, v197
	v_mul_f32_e32 v172, v39, v205
	v_mul_f32_e32 v160, v54, v197
	v_mul_f32_e32 v173, v38, v205
	v_mul_f32_e32 v161, v54, v196
	v_mul_f32_e32 v174, v38, v204
	v_mul_f32_e32 v170, v199, v57
	v_mul_f32_e32 v175, v207, v41
	v_mul_f32_e32 v171, v56, v199
	v_mul_f32_e32 v176, v40, v207
	v_fma_f32 v55, v55, v196, v160
	v_fma_f32 v39, v39, v204, v173
	v_sub_f32_e32 v54, v161, v0
	v_sub_f32_e32 v38, v174, v172
	v_fma_f32 v56, v198, v56, -v170
	v_fma_f32 v40, v206, v40, -v175
	v_fma_f32 v57, v57, v198, v171
	v_fma_f32 v41, v41, v206, v176
	v_mul_f32_e32 v0, v23, v197
	v_mul_f32_e32 v172, v7, v205
	v_mul_f32_e32 v160, v22, v197
	v_mul_f32_e32 v173, v6, v205
	v_mul_f32_e32 v161, v22, v196
	v_mul_f32_e32 v174, v6, v204
	v_mul_f32_e32 v170, v199, v25
	v_mul_f32_e32 v175, v207, v9
	v_mul_f32_e32 v171, v24, v199
	v_mul_f32_e32 v176, v8, v207
	v_fma_f32 v23, v23, v196, v160
	v_fma_f32 v7, v7, v204, v173
	v_sub_f32_e32 v22, v161, v0
	v_sub_f32_e32 v6, v174, v172
	v_fma_f32 v24, v198, v24, -v170
	v_fma_f32 v8, v206, v8, -v175
	v_fma_f32 v25, v25, v198, v171
	v_fma_f32 v9, v9, v206, v176
	s_waitcnt vmcnt(0)
; __device__ __forceinline__ unsigned cvt_pk_bf16(float lo, float hi) { unsigned r; asm volatile("v_cvt_pk_bf16_f32 %0, %1, %2" : "=v"(r) : "v"(lo), "v"(hi)); return r; }
;     __device__ __forceinline__ void operator()(AccT& acc, const Unit& u, int wr, int wc, int fr, int fq) const {
;     ...
;             for (int m = 0; m < 4; ++m) { const int row = row0 + ai * 128 + m * 16; bf16_t* rowp = O + (size_t)row * NPROJ + col0;
;                 f32x4 cs0 = (f32x4){1.f, 0.f, 1.f, 0.f}, cs1 = cs0;
;                 if (rot) { const int pos = row < HALF_TOK ? (row & 8191) : ((row - HALF_TOK) & 2047); const f32x2* rp = rope + (size_t)pos * 64 + i0; cs0 = *(const f32x4*)rp; cs1 = *(const f32x4*)(rp + 2); }
; #pragma unroll
;                 for (int bj = 0; bj < 2; ++bj) { f32x4 v0 = acc[ai][bj][m][0], v1 = acc[ai][bj][m][1];
;                     if (rot) { const f32x4 a = v0, b = v1;
;                         v0[0] = a[0] * cs0[0] - a[1] * cs0[1]; v0[1] = a[1] * cs0[0] + a[0] * cs0[1]; v0[2] = a[2] * cs0[2] - a[3] * cs0[3]; v0[3] = a[3] * cs0[2] + a[2] * cs0[3];
;                         v1[0] = b[0] * cs1[0] - b[1] * cs1[1]; v1[1] = b[1] * cs1[0] + b[0] * cs1[1]; v1[2] = b[2] * cs1[2] - b[3] * cs1[3]; v1[3] = b[3] * cs1[2] + b[2] * cs1[3]; }
;                     u32x4 w; w.x = cvt_pk_bf16(v0[0], v0[1]); w.y = cvt_pk_bf16(v0[2], v0[3]); w.z = cvt_pk_bf16(v1[0], v1[1]); w.w = cvt_pk_bf16(v1[2], v1[3]);
;                     *(u32x4*)(rowp + bj * 128) = w; }
	v_mul_f32_e32 v0, v51, v223
	v_mul_f32_e32 v172, v35, v227
	v_mul_f32_e32 v160, v50, v223
	v_mul_f32_e32 v173, v34, v227
	v_mul_f32_e32 v161, v50, v222
	v_mul_f32_e32 v174, v34, v226
	v_mul_f32_e32 v170, v225, v53
	v_mul_f32_e32 v175, v229, v37
	v_mul_f32_e32 v171, v52, v225
	v_mul_f32_e32 v176, v36, v229
	v_fma_f32 v51, v51, v222, v160
	v_fma_f32 v35, v35, v226, v173
	v_sub_f32_e32 v50, v161, v0
	v_sub_f32_e32 v34, v174, v172
	v_fma_f32 v52, v224, v52, -v170
	v_fma_f32 v36, v228, v36, -v175
	v_fma_f32 v53, v53, v224, v171
	v_fma_f32 v37, v37, v228, v176
	v_mul_f32_e32 v0, v19, v223
	v_mul_f32_e32 v172, v3, v227
	v_mul_f32_e32 v160, v18, v223
	v_mul_f32_e32 v173, v2, v227
	v_mul_f32_e32 v161, v18, v222
	v_mul_f32_e32 v174, v2, v226
	v_mul_f32_e32 v170, v225, v21
	v_mul_f32_e32 v175, v229, v5
	v_mul_f32_e32 v171, v20, v225
	v_mul_f32_e32 v176, v4, v229
	v_fma_f32 v19, v19, v222, v160
	v_fma_f32 v3, v3, v226, v173
	v_sub_f32_e32 v18, v161, v0
	v_sub_f32_e32 v2, v174, v172
	v_fma_f32 v20, v224, v20, -v170
	v_fma_f32 v4, v228, v4, -v175
	v_fma_f32 v21, v21, v224, v171
	v_fma_f32 v5, v5, v228, v176
	v_cvt_pk_bf16_f32 v164, v126, v127
	v_cvt_pk_bf16_f32 v165, v128, v129
	v_cvt_pk_bf16_f32 v166, v110, v111
	v_cvt_pk_bf16_f32 v167, v112, v113
	global_store_dwordx4 v[142:143], v[164:167], off nt
	v_cvt_pk_bf16_f32 v178, v94, v95
	v_cvt_pk_bf16_f32 v179, v96, v97
	v_cvt_pk_bf16_f32 v180, v78, v79
	v_cvt_pk_bf16_f32 v181, v80, v81
	global_store_dwordx4 v[142:143], v[178:181], off offset:256 nt
	v_lshl_add_u64 v[144:145], v[142:143], 0, s[2:3]
	v_cvt_pk_bf16_f32 v164, v122, v123
	v_cvt_pk_bf16_f32 v165, v124, v125
	v_cvt_pk_bf16_f32 v166, v106, v107
	v_cvt_pk_bf16_f32 v167, v108, v109
	global_store_dwordx4 v[144:145], v[164:167], off nt
	v_cvt_pk_bf16_f32 v178, v90, v91
	v_cvt_pk_bf16_f32 v179, v92, v93
	v_cvt_pk_bf16_f32 v180, v74, v75
	v_cvt_pk_bf16_f32 v181, v76, v77
	global_store_dwordx4 v[144:145], v[178:181], off offset:256 nt
	v_lshl_add_u64 v[142:143], v[144:145], 0, s[2:3]
	v_cvt_pk_bf16_f32 v164, v118, v119
	v_cvt_pk_bf16_f32 v165, v120, v121
	v_cvt_pk_bf16_f32 v166, v102, v103
	v_cvt_pk_bf16_f32 v167, v104, v105
	global_store_dwordx4 v[142:143], v[164:167], off nt
	v_cvt_pk_bf16_f32 v178, v86, v87
	v_cvt_pk_bf16_f32 v179, v88, v89
	v_cvt_pk_bf16_f32 v180, v70, v71
	v_cvt_pk_bf16_f32 v181, v72, v73
	global_store_dwordx4 v[142:143], v[178:181], off offset:256 nt
	v_lshl_add_u64 v[144:145], v[142:143], 0, s[2:3]
	v_cvt_pk_bf16_f32 v164, v114, v115
	v_cvt_pk_bf16_f32 v165, v116, v117
	v_cvt_pk_bf16_f32 v166, v98, v99
	v_cvt_pk_bf16_f32 v167, v100, v101
	global_store_dwordx4 v[144:145], v[164:167], off nt
	v_cvt_pk_bf16_f32 v178, v82, v83
	v_cvt_pk_bf16_f32 v179, v84, v85
	v_cvt_pk_bf16_f32 v180, v66, v67
	v_cvt_pk_bf16_f32 v181, v68, v69
	global_store_dwordx4 v[144:145], v[178:181], off offset:256 nt
	v_lshl_add_u64 v[142:143], v[144:145], 0, s[2:3]
	v_lshl_add_u64 v[142:143], v[142:143], 0, s[2:3]
	v_lshl_add_u64 v[142:143], v[142:143], 0, s[2:3]
	v_lshl_add_u64 v[142:143], v[142:143], 0, s[2:3]
	v_lshl_add_u64 v[142:143], v[142:143], 0, s[2:3]
	v_cvt_pk_bf16_f32 v164, v62, v63
	v_cvt_pk_bf16_f32 v165, v64, v65
	v_cvt_pk_bf16_f32 v166, v46, v47
	v_cvt_pk_bf16_f32 v167, v48, v49
	global_store_dwordx4 v[142:143], v[164:167], off nt
	v_cvt_pk_bf16_f32 v178, v30, v31
	v_cvt_pk_bf16_f32 v179, v32, v33
	v_cvt_pk_bf16_f32 v180, v14, v15
	v_cvt_pk_bf16_f32 v181, v16, v17
	global_store_dwordx4 v[142:143], v[178:181], off offset:256 nt
	v_lshl_add_u64 v[144:145], v[142:143], 0, s[2:3]
	v_cvt_pk_bf16_f32 v164, v58, v59
	v_cvt_pk_bf16_f32 v165, v60, v61
	v_cvt_pk_bf16_f32 v166, v42, v43
	v_cvt_pk_bf16_f32 v167, v44, v45
	global_store_dwordx4 v[144:145], v[164:167], off nt
	v_cvt_pk_bf16_f32 v178, v26, v27
	v_cvt_pk_bf16_f32 v179, v28, v29
	v_cvt_pk_bf16_f32 v180, v10, v11
	v_cvt_pk_bf16_f32 v181, v12, v13
	global_store_dwordx4 v[144:145], v[178:181], off offset:256 nt
	v_lshl_add_u64 v[142:143], v[144:145], 0, s[2:3]
	v_cvt_pk_bf16_f32 v164, v54, v55
	v_cvt_pk_bf16_f32 v165, v56, v57
	v_cvt_pk_bf16_f32 v166, v38, v39
	v_cvt_pk_bf16_f32 v167, v40, v41
	global_store_dwordx4 v[142:143], v[164:167], off nt
	v_cvt_pk_bf16_f32 v178, v22, v23
	v_cvt_pk_bf16_f32 v179, v24, v25
	v_cvt_pk_bf16_f32 v180, v6, v7
	v_cvt_pk_bf16_f32 v181, v8, v9
	global_store_dwordx4 v[142:143], v[178:181], off offset:256 nt
	v_lshl_add_u64 v[144:145], v[142:143], 0, s[2:3]
	v_cvt_pk_bf16_f32 v164, v50, v51
	v_cvt_pk_bf16_f32 v165, v52, v53
	v_cvt_pk_bf16_f32 v166, v34, v35
	v_cvt_pk_bf16_f32 v167, v36, v37
	global_store_dwordx4 v[144:145], v[164:167], off nt
	v_cvt_pk_bf16_f32 v178, v18, v19
	v_cvt_pk_bf16_f32 v179, v20, v21
	v_cvt_pk_bf16_f32 v180, v2, v3
	v_cvt_pk_bf16_f32 v181, v4, v5
	global_store_dwordx4 v[144:145], v[178:181], off offset:256 nt
